# v8 plus in-proj loop: A-fragment LDS base folded into ds_read offsets (4 VALU adds dropped) and 6 duplicate lgkmcnt(0) waits dropped
# speedup vs baseline: 1.0123x; 1.0014x over previous
.LBB0_258:
	s_ashr_i32 s19, s18, 31
	v_cmp_lt_i64_e32 vcc, s[20:21], v[214:215]
	s_lshl_b64 s[20:21], s[18:19], 20
	s_add_u32 s20, s94, s20
	s_addc_u32 s21, s95, s21
	s_and_b64 s[22:23], vcc, exec
	s_cselect_b32 s19, s21, s41
	s_cselect_b32 s24, s20, s40
	s_ashr_i32 s17, s16, 31
	s_lshl_b64 s[22:23], s[16:17], 20
	s_add_u32 s22, s49, s22
	s_addc_u32 s23, s52, s23
	s_and_b64 s[44:45], vcc, exec
	s_cselect_b32 s17, s23, s43
	s_cselect_b32 s25, s22, s42
	s_add_u32 s40, s40, 0x80080
	s_addc_u32 s41, s41, 0
	s_add_u32 s33, s42, 0x100
	v_mov_b32_e32 v2, 0
	s_addc_u32 s80, s43, 0
	s_mov_b32 s81, -2
	v_mov_b32_e32 v3, v2
	v_mov_b32_e32 v4, v2
	v_mov_b32_e32 v5, v2
	v_mov_b32_e32 v6, v2
	v_mov_b32_e32 v7, v2
	v_mov_b32_e32 v8, v2
	v_mov_b32_e32 v9, v2
	v_mov_b32_e32 v18, v2
	v_mov_b32_e32 v19, v2
	v_mov_b32_e32 v20, v2
	v_mov_b32_e32 v21, v2
	v_mov_b32_e32 v22, v2
	v_mov_b32_e32 v23, v2
	v_mov_b32_e32 v24, v2
	v_mov_b32_e32 v25, v2
	v_mov_b32_e32 v34, v2
	v_mov_b32_e32 v35, v2
	v_mov_b32_e32 v36, v2
	v_mov_b32_e32 v37, v2
	v_mov_b32_e32 v38, v2
	v_mov_b32_e32 v39, v2
	v_mov_b32_e32 v40, v2
	v_mov_b32_e32 v41, v2
	v_mov_b32_e32 v50, v2
	v_mov_b32_e32 v51, v2
	v_mov_b32_e32 v52, v2
	v_mov_b32_e32 v53, v2
	v_mov_b32_e32 v54, v2
	v_mov_b32_e32 v55, v2
	v_mov_b32_e32 v56, v2
	v_mov_b32_e32 v57, v2
	v_mov_b32_e32 v10, v2
	v_mov_b32_e32 v11, v2
	v_mov_b32_e32 v12, v2
	v_mov_b32_e32 v13, v2
	v_mov_b32_e32 v14, v2
	v_mov_b32_e32 v15, v2
	v_mov_b32_e32 v16, v2
	v_mov_b32_e32 v17, v2
	v_mov_b32_e32 v26, v2
	v_mov_b32_e32 v27, v2
	v_mov_b32_e32 v28, v2
	v_mov_b32_e32 v29, v2
	v_mov_b32_e32 v30, v2
	v_mov_b32_e32 v31, v2
	v_mov_b32_e32 v32, v2
	v_mov_b32_e32 v33, v2
	v_mov_b32_e32 v42, v2
	v_mov_b32_e32 v43, v2
	v_mov_b32_e32 v44, v2
	v_mov_b32_e32 v45, v2
	v_mov_b32_e32 v46, v2
	v_mov_b32_e32 v47, v2
	v_mov_b32_e32 v48, v2
	v_mov_b32_e32 v49, v2
	v_mov_b32_e32 v58, v2
	v_mov_b32_e32 v59, v2
	v_mov_b32_e32 v60, v2
	v_mov_b32_e32 v61, v2
	v_mov_b32_e32 v62, v2
	v_mov_b32_e32 v63, v2
	v_mov_b32_e32 v64, v2
	v_mov_b32_e32 v65, v2
	v_mov_b32_e32 v66, v2
	v_mov_b32_e32 v67, v2
	v_mov_b32_e32 v68, v2
	v_mov_b32_e32 v69, v2
	v_mov_b32_e32 v70, v2
	v_mov_b32_e32 v71, v2
	v_mov_b32_e32 v72, v2
	v_mov_b32_e32 v73, v2
	v_mov_b32_e32 v82, v2
	v_mov_b32_e32 v83, v2
	v_mov_b32_e32 v84, v2
	v_mov_b32_e32 v85, v2
	v_mov_b32_e32 v86, v2
	v_mov_b32_e32 v87, v2
	v_mov_b32_e32 v88, v2
	v_mov_b32_e32 v89, v2
	v_mov_b32_e32 v98, v2
	v_mov_b32_e32 v99, v2
	v_mov_b32_e32 v100, v2
	v_mov_b32_e32 v101, v2
	v_mov_b32_e32 v102, v2
	v_mov_b32_e32 v103, v2
	v_mov_b32_e32 v104, v2
	v_mov_b32_e32 v105, v2
	v_mov_b32_e32 v114, v2
	v_mov_b32_e32 v115, v2
	v_mov_b32_e32 v116, v2
	v_mov_b32_e32 v117, v2
	v_mov_b32_e32 v118, v2
	v_mov_b32_e32 v119, v2
	v_mov_b32_e32 v120, v2
	v_mov_b32_e32 v121, v2
	v_mov_b32_e32 v74, v2
	v_mov_b32_e32 v75, v2
	v_mov_b32_e32 v76, v2
	v_mov_b32_e32 v77, v2
	v_mov_b32_e32 v78, v2
	v_mov_b32_e32 v79, v2
	v_mov_b32_e32 v80, v2
	v_mov_b32_e32 v81, v2
	v_mov_b32_e32 v90, v2
	v_mov_b32_e32 v91, v2
	v_mov_b32_e32 v92, v2
	v_mov_b32_e32 v93, v2
	v_mov_b32_e32 v94, v2
	v_mov_b32_e32 v95, v2
	v_mov_b32_e32 v96, v2
	v_mov_b32_e32 v97, v2
	v_mov_b32_e32 v106, v2
	v_mov_b32_e32 v107, v2
	v_mov_b32_e32 v108, v2
	v_mov_b32_e32 v109, v2
	v_mov_b32_e32 v110, v2
	v_mov_b32_e32 v111, v2
	v_mov_b32_e32 v112, v2
	v_mov_b32_e32 v113, v2
	v_mov_b32_e32 v122, v2
	v_mov_b32_e32 v123, v2
	v_mov_b32_e32 v124, v2
	v_mov_b32_e32 v125, v2
	v_mov_b32_e32 v126, v2
	v_mov_b32_e32 v127, v2
	v_mov_b32_e32 v128, v2
	v_mov_b32_e32 v129, v2
	v_add_u32_e32 v146, 0x10000, v147
.LBB0_259:
	s_add_u32 s13, s40, 0xfff80080
	s_addc_u32 s36, s41, -1
	s_add_i32 s37, 0, 0x10000
	ds_read_b128 v[142:145], v146
	ds_read_b128 v[152:155], v146 offset:1024
	ds_read_b128 v[156:159], v146 offset:2048
	ds_read_b128 v[160:163], v146 offset:3072
	s_cmp_eq_u32 s81, 28
	s_cselect_b32 s45, s19, s36
	s_cselect_b32 s44, s24, s13
	s_cselect_b32 s43, s17, s80
	s_cselect_b32 s42, s25, s33
	s_add_i32 m0, s69, 0xc000
	ds_read_b128 v[164:167], v150
	ds_read_b128 v[168:171], v150 offset:1024
	ds_read_b128 v[172:175], v150 offset:2048
	ds_read_b128 v[176:179], v150 offset:3072
	ds_read_b128 v[180:183], v150 offset:4096
	ds_read_b128 v[184:187], v150 offset:5120
	ds_read_b128 v[188:191], v150 offset:6144
	ds_read_b128 v[192:195], v150 offset:7168
	global_load_lds_dwordx4 v138, s[40:41]
	s_add_i32 m0, s69, 0xe000
	s_nop 0
	global_load_lds_dwordx4 v140, s[40:41]
	s_waitcnt lgkmcnt(8)
	s_barrier
	s_waitcnt lgkmcnt(0)
	v_mfma_f32_16x16x32_bf16 v[126:129], v[142:145], v[164:167], v[126:129]
	v_mfma_f32_16x16x32_bf16 v[122:125], v[156:159], v[164:167], v[122:125]
	v_mfma_f32_16x16x32_bf16 v[110:113], v[142:145], v[172:175], v[110:113]
	v_mfma_f32_16x16x32_bf16 v[106:109], v[156:159], v[172:175], v[106:109]
	v_mfma_f32_16x16x32_bf16 v[94:97], v[142:145], v[180:183], v[94:97]
	v_mfma_f32_16x16x32_bf16 v[90:93], v[156:159], v[180:183], v[90:93]
	v_mfma_f32_16x16x32_bf16 v[78:81], v[142:145], v[188:191], v[78:81]
	v_mfma_f32_16x16x32_bf16 v[74:77], v[156:159], v[188:191], v[74:77]
	v_mfma_f32_16x16x32_bf16 v[126:129], v[152:155], v[168:171], v[126:129]
	v_mfma_f32_16x16x32_bf16 v[122:125], v[160:163], v[168:171], v[122:125]
	v_mfma_f32_16x16x32_bf16 v[110:113], v[152:155], v[176:179], v[110:113]
	v_mfma_f32_16x16x32_bf16 v[106:109], v[160:163], v[176:179], v[106:109]
	v_mfma_f32_16x16x32_bf16 v[94:97], v[152:155], v[184:187], v[94:97]
	v_mfma_f32_16x16x32_bf16 v[90:93], v[160:163], v[184:187], v[90:93]
	v_mfma_f32_16x16x32_bf16 v[78:81], v[152:155], v[192:195], v[78:81]
	v_mfma_f32_16x16x32_bf16 v[74:77], v[160:163], v[192:195], v[74:77]
	s_barrier
	s_add_i32 s13, 0, 0x14000
	s_add_i32 s36, s37, s48
	v_lshl_add_u64 v[204:205], s[42:43], 0, v[134:135]
	s_mov_b32 m0, s36
	ds_read_b128 v[196:199], v146 offset:16384
	ds_read_b128 v[200:203], v146 offset:17408
	ds_read_b128 v[216:219], v146 offset:18432
	ds_read_b128 v[232:235], v146 offset:19456
	global_load_lds_dwordx4 v[204:205], off
	v_lshl_add_u64 v[236:237], s[42:43], 0, v[130:131]
	s_add_i32 m0, s36, 0x2000
	s_nop 0
	global_load_lds_dwordx4 v[236:237], off
	s_barrier
	s_waitcnt lgkmcnt(0)
	v_mfma_f32_16x16x32_bf16 v[118:121], v[196:199], v[164:167], v[118:121]
	v_mfma_f32_16x16x32_bf16 v[114:117], v[216:219], v[164:167], v[114:117]
	v_mfma_f32_16x16x32_bf16 v[102:105], v[196:199], v[172:175], v[102:105]
	v_mfma_f32_16x16x32_bf16 v[98:101], v[216:219], v[172:175], v[98:101]
	v_mfma_f32_16x16x32_bf16 v[86:89], v[196:199], v[180:183], v[86:89]
	v_mfma_f32_16x16x32_bf16 v[82:85], v[216:219], v[180:183], v[82:85]
	v_mfma_f32_16x16x32_bf16 v[70:73], v[196:199], v[188:191], v[70:73]
	v_mfma_f32_16x16x32_bf16 v[66:69], v[216:219], v[188:191], v[66:69]
	v_mfma_f32_16x16x32_bf16 v[118:121], v[200:203], v[168:171], v[118:121]
	v_mfma_f32_16x16x32_bf16 v[114:117], v[232:235], v[168:171], v[114:117]
	v_mfma_f32_16x16x32_bf16 v[102:105], v[200:203], v[176:179], v[102:105]
	v_mfma_f32_16x16x32_bf16 v[98:101], v[232:235], v[176:179], v[98:101]
	v_mfma_f32_16x16x32_bf16 v[86:89], v[200:203], v[184:187], v[86:89]
	v_mfma_f32_16x16x32_bf16 v[82:85], v[232:235], v[184:187], v[82:85]
	v_mfma_f32_16x16x32_bf16 v[70:73], v[200:203], v[192:195], v[70:73]
	v_mfma_f32_16x16x32_bf16 v[66:69], v[232:235], v[192:195], v[66:69]
	s_mov_b32 m0, s69
	v_lshl_add_u64 v[238:239], s[44:45], 0, v[136:137]
	s_barrier
	ds_read_b128 v[164:167], v150 offset:16384
	ds_read_b128 v[168:171], v150 offset:17408
	ds_read_b128 v[172:175], v150 offset:18432
	ds_read_b128 v[176:179], v150 offset:19456
	ds_read_b128 v[180:183], v150 offset:20480
	ds_read_b128 v[184:187], v150 offset:21504
	ds_read_b128 v[188:191], v150 offset:22528
	ds_read_b128 v[192:195], v150 offset:23552
	global_load_lds_dwordx4 v[238:239], off
	v_lshl_add_u64 v[240:241], s[44:45], 0, v[132:133]
	s_mov_b32 m0, s86
	s_nop 0
	global_load_lds_dwordx4 v[240:241], off
	s_barrier
	s_waitcnt lgkmcnt(0)
	v_mfma_f32_16x16x32_bf16 v[62:65], v[142:145], v[164:167], v[62:65]
	v_mfma_f32_16x16x32_bf16 v[58:61], v[156:159], v[164:167], v[58:61]
	v_mfma_f32_16x16x32_bf16 v[46:49], v[142:145], v[172:175], v[46:49]
	v_mfma_f32_16x16x32_bf16 v[42:45], v[156:159], v[172:175], v[42:45]
	v_mfma_f32_16x16x32_bf16 v[30:33], v[142:145], v[180:183], v[30:33]
	v_mfma_f32_16x16x32_bf16 v[26:29], v[156:159], v[180:183], v[26:29]
	v_mfma_f32_16x16x32_bf16 v[14:17], v[142:145], v[188:191], v[14:17]
	v_mfma_f32_16x16x32_bf16 v[10:13], v[156:159], v[188:191], v[10:13]
	v_mfma_f32_16x16x32_bf16 v[62:65], v[152:155], v[168:171], v[62:65]
	v_mfma_f32_16x16x32_bf16 v[58:61], v[160:163], v[168:171], v[58:61]
	v_mfma_f32_16x16x32_bf16 v[46:49], v[152:155], v[176:179], v[46:49]
	v_mfma_f32_16x16x32_bf16 v[42:45], v[160:163], v[176:179], v[42:45]
	v_mfma_f32_16x16x32_bf16 v[30:33], v[152:155], v[184:187], v[30:33]
	v_mfma_f32_16x16x32_bf16 v[26:29], v[160:163], v[184:187], v[26:29]
	v_mfma_f32_16x16x32_bf16 v[14:17], v[152:155], v[192:195], v[14:17]
	v_mfma_f32_16x16x32_bf16 v[10:13], v[160:163], v[192:195], v[10:13]
	s_barrier
	s_add_u32 s96, s42, 0x80000
	s_addc_u32 s97, s43, 0
	s_add_i32 s13, s13, s48
	s_mov_b32 m0, s13
	s_nop 0
	global_load_lds_dwordx4 v134, s[96:97]
	s_add_i32 m0, s13, 0x2000
	s_nop 0
	global_load_lds_dwordx4 v130, s[96:97]
	s_waitcnt vmcnt(6)
	s_barrier
	v_mfma_f32_16x16x32_bf16 v[54:57], v[196:199], v[164:167], v[54:57]
	v_mfma_f32_16x16x32_bf16 v[50:53], v[216:219], v[164:167], v[50:53]
	v_mfma_f32_16x16x32_bf16 v[38:41], v[196:199], v[172:175], v[38:41]
	v_mfma_f32_16x16x32_bf16 v[34:37], v[216:219], v[172:175], v[34:37]
	v_mfma_f32_16x16x32_bf16 v[22:25], v[196:199], v[180:183], v[22:25]
	v_mfma_f32_16x16x32_bf16 v[18:21], v[216:219], v[180:183], v[18:21]
	v_mfma_f32_16x16x32_bf16 v[6:9], v[196:199], v[188:191], v[6:9]
	v_mfma_f32_16x16x32_bf16 v[2:5], v[216:219], v[188:191], v[2:5]
	v_mfma_f32_16x16x32_bf16 v[54:57], v[200:203], v[168:171], v[54:57]
	v_mfma_f32_16x16x32_bf16 v[50:53], v[232:235], v[168:171], v[50:53]
	v_mfma_f32_16x16x32_bf16 v[38:41], v[200:203], v[176:179], v[38:41]
	v_mfma_f32_16x16x32_bf16 v[34:37], v[232:235], v[176:179], v[34:37]
	v_mfma_f32_16x16x32_bf16 v[22:25], v[200:203], v[184:187], v[22:25]
	v_mfma_f32_16x16x32_bf16 v[18:21], v[232:235], v[184:187], v[18:21]
	v_mfma_f32_16x16x32_bf16 v[6:9], v[200:203], v[192:195], v[6:9]
	v_mfma_f32_16x16x32_bf16 v[2:5], v[232:235], v[192:195], v[2:5]
	s_add_i32 s13, 0, 0x18000
	s_barrier
	ds_read_b128 v[142:145], v146 offset:32768
	ds_read_b128 v[152:155], v146 offset:33792
	ds_read_b128 v[156:159], v146 offset:34816
	ds_read_b128 v[160:163], v146 offset:35840
	s_add_u32 s44, s44, 0x80000
	s_addc_u32 s45, s45, 0
	s_mov_b32 m0, s87
	ds_read_b128 v[164:167], v150 offset:32768
	ds_read_b128 v[168:171], v150 offset:33792
	ds_read_b128 v[172:175], v150 offset:34816
	ds_read_b128 v[176:179], v150 offset:35840
	ds_read_b128 v[180:183], v150 offset:36864
	ds_read_b128 v[184:187], v150 offset:37888
	ds_read_b128 v[188:191], v150 offset:38912
	ds_read_b128 v[192:195], v150 offset:39936
	global_load_lds_dwordx4 v136, s[44:45]
	s_mov_b32 m0, s90
	s_nop 0
	global_load_lds_dwordx4 v132, s[44:45]
	s_waitcnt lgkmcnt(8)
	s_barrier
	s_waitcnt lgkmcnt(0)
	v_mfma_f32_16x16x32_bf16 v[126:129], v[142:145], v[164:167], v[126:129]
	v_mfma_f32_16x16x32_bf16 v[122:125], v[156:159], v[164:167], v[122:125]
	v_mfma_f32_16x16x32_bf16 v[110:113], v[142:145], v[172:175], v[110:113]
	v_mfma_f32_16x16x32_bf16 v[106:109], v[156:159], v[172:175], v[106:109]
	v_mfma_f32_16x16x32_bf16 v[94:97], v[142:145], v[180:183], v[94:97]
	v_mfma_f32_16x16x32_bf16 v[90:93], v[156:159], v[180:183], v[90:93]
	v_mfma_f32_16x16x32_bf16 v[78:81], v[142:145], v[188:191], v[78:81]
	v_mfma_f32_16x16x32_bf16 v[74:77], v[156:159], v[188:191], v[74:77]
	v_mfma_f32_16x16x32_bf16 v[126:129], v[152:155], v[168:171], v[126:129]
	v_mfma_f32_16x16x32_bf16 v[122:125], v[160:163], v[168:171], v[122:125]
	v_mfma_f32_16x16x32_bf16 v[110:113], v[152:155], v[176:179], v[110:113]
	v_mfma_f32_16x16x32_bf16 v[106:109], v[160:163], v[176:179], v[106:109]
	v_mfma_f32_16x16x32_bf16 v[94:97], v[152:155], v[184:187], v[94:97]
	v_mfma_f32_16x16x32_bf16 v[90:93], v[160:163], v[184:187], v[90:93]
	v_mfma_f32_16x16x32_bf16 v[78:81], v[152:155], v[192:195], v[78:81]
	v_mfma_f32_16x16x32_bf16 v[74:77], v[160:163], v[192:195], v[74:77]
	s_barrier
	s_add_i32 s36, 0, 0x1c000
	s_add_i32 s13, s13, s48
	v_lshl_add_u64 v[204:205], v[204:205], 0, s[14:15]
	s_mov_b32 m0, s13
	ds_read_b128 v[196:199], v146 offset:49152
	ds_read_b128 v[200:203], v146 offset:50176
	ds_read_b128 v[216:219], v146 offset:51200
	ds_read_b128 v[232:235], v146 offset:52224
	global_load_lds_dwordx4 v[204:205], off
	v_lshl_add_u64 v[204:205], v[236:237], 0, s[14:15]
	s_add_i32 m0, s13, 0x2000
	s_nop 0
	global_load_lds_dwordx4 v[204:205], off
	s_barrier
	s_waitcnt lgkmcnt(0)
	v_mfma_f32_16x16x32_bf16 v[118:121], v[196:199], v[164:167], v[118:121]
	v_mfma_f32_16x16x32_bf16 v[114:117], v[216:219], v[164:167], v[114:117]
	v_mfma_f32_16x16x32_bf16 v[102:105], v[196:199], v[172:175], v[102:105]
	v_mfma_f32_16x16x32_bf16 v[98:101], v[216:219], v[172:175], v[98:101]
	v_mfma_f32_16x16x32_bf16 v[86:89], v[196:199], v[180:183], v[86:89]
	v_mfma_f32_16x16x32_bf16 v[82:85], v[216:219], v[180:183], v[82:85]
	v_mfma_f32_16x16x32_bf16 v[70:73], v[196:199], v[188:191], v[70:73]
	v_mfma_f32_16x16x32_bf16 v[66:69], v[216:219], v[188:191], v[66:69]
	v_mfma_f32_16x16x32_bf16 v[118:121], v[200:203], v[168:171], v[118:121]
	v_mfma_f32_16x16x32_bf16 v[114:117], v[232:235], v[168:171], v[114:117]
	v_mfma_f32_16x16x32_bf16 v[102:105], v[200:203], v[176:179], v[102:105]
	v_mfma_f32_16x16x32_bf16 v[98:101], v[232:235], v[176:179], v[98:101]
	v_mfma_f32_16x16x32_bf16 v[86:89], v[200:203], v[184:187], v[86:89]
	v_mfma_f32_16x16x32_bf16 v[82:85], v[232:235], v[184:187], v[82:85]
	v_mfma_f32_16x16x32_bf16 v[70:73], v[200:203], v[192:195], v[70:73]
	v_mfma_f32_16x16x32_bf16 v[66:69], v[232:235], v[192:195], v[66:69]
	s_mov_b32 m0, s91
	v_lshl_add_u64 v[204:205], v[238:239], 0, s[14:15]
	s_barrier
	ds_read_b128 v[164:167], v150 offset:49152
	ds_read_b128 v[168:171], v150 offset:50176
	ds_read_b128 v[172:175], v150 offset:51200
	ds_read_b128 v[176:179], v150 offset:52224
	ds_read_b128 v[180:183], v150 offset:53248
	ds_read_b128 v[184:187], v150 offset:54272
	ds_read_b128 v[188:191], v150 offset:55296
	ds_read_b128 v[192:195], v150 offset:56320
	global_load_lds_dwordx4 v[204:205], off
	v_lshl_add_u64 v[204:205], v[240:241], 0, s[14:15]
	s_mov_b32 m0, s26
	s_nop 0
	global_load_lds_dwordx4 v[204:205], off
	s_barrier
	s_waitcnt lgkmcnt(0)
	v_mfma_f32_16x16x32_bf16 v[62:65], v[142:145], v[164:167], v[62:65]
	v_mfma_f32_16x16x32_bf16 v[58:61], v[156:159], v[164:167], v[58:61]
	v_mfma_f32_16x16x32_bf16 v[46:49], v[142:145], v[172:175], v[46:49]
	v_mfma_f32_16x16x32_bf16 v[42:45], v[156:159], v[172:175], v[42:45]
	v_mfma_f32_16x16x32_bf16 v[30:33], v[142:145], v[180:183], v[30:33]
	v_mfma_f32_16x16x32_bf16 v[26:29], v[156:159], v[180:183], v[26:29]
	v_mfma_f32_16x16x32_bf16 v[14:17], v[142:145], v[188:191], v[14:17]
	v_mfma_f32_16x16x32_bf16 v[10:13], v[156:159], v[188:191], v[10:13]
	v_mfma_f32_16x16x32_bf16 v[62:65], v[152:155], v[168:171], v[62:65]
	v_mfma_f32_16x16x32_bf16 v[58:61], v[160:163], v[168:171], v[58:61]
	v_mfma_f32_16x16x32_bf16 v[46:49], v[152:155], v[176:179], v[46:49]
	v_mfma_f32_16x16x32_bf16 v[42:45], v[160:163], v[176:179], v[42:45]
	v_mfma_f32_16x16x32_bf16 v[30:33], v[152:155], v[184:187], v[30:33]
	v_mfma_f32_16x16x32_bf16 v[26:29], v[160:163], v[184:187], v[26:29]
	v_mfma_f32_16x16x32_bf16 v[14:17], v[152:155], v[192:195], v[14:17]
	v_mfma_f32_16x16x32_bf16 v[10:13], v[160:163], v[192:195], v[10:13]
	s_barrier
	s_add_u32 s42, s42, 0x80080
	s_addc_u32 s43, s43, 0
	s_add_i32 s13, s36, s48
	s_mov_b32 m0, s13
	s_nop 0
	global_load_lds_dwordx4 v134, s[42:43]
	s_add_i32 m0, s13, 0x2000
	s_nop 0
	global_load_lds_dwordx4 v130, s[42:43]
	s_waitcnt vmcnt(6)
	s_barrier
	v_mfma_f32_16x16x32_bf16 v[54:57], v[196:199], v[164:167], v[54:57]
	v_mfma_f32_16x16x32_bf16 v[50:53], v[216:219], v[164:167], v[50:53]
	v_mfma_f32_16x16x32_bf16 v[38:41], v[196:199], v[172:175], v[38:41]
	v_mfma_f32_16x16x32_bf16 v[34:37], v[216:219], v[172:175], v[34:37]
	v_mfma_f32_16x16x32_bf16 v[22:25], v[196:199], v[180:183], v[22:25]
	v_mfma_f32_16x16x32_bf16 v[18:21], v[216:219], v[180:183], v[18:21]
	v_mfma_f32_16x16x32_bf16 v[6:9], v[196:199], v[188:191], v[6:9]
	v_mfma_f32_16x16x32_bf16 v[2:5], v[216:219], v[188:191], v[2:5]
	v_mfma_f32_16x16x32_bf16 v[54:57], v[200:203], v[168:171], v[54:57]
	v_mfma_f32_16x16x32_bf16 v[50:53], v[232:235], v[168:171], v[50:53]
	v_mfma_f32_16x16x32_bf16 v[38:41], v[200:203], v[176:179], v[38:41]
	v_mfma_f32_16x16x32_bf16 v[34:37], v[232:235], v[176:179], v[34:37]
	v_mfma_f32_16x16x32_bf16 v[22:25], v[200:203], v[184:187], v[22:25]
	v_mfma_f32_16x16x32_bf16 v[18:21], v[232:235], v[184:187], v[18:21]
	v_mfma_f32_16x16x32_bf16 v[6:9], v[200:203], v[192:195], v[6:9]
	v_mfma_f32_16x16x32_bf16 v[2:5], v[232:235], v[192:195], v[2:5]
	s_add_i32 s81, s81, 2
	s_add_u32 s40, s40, 0x100
	s_addc_u32 s41, s41, 0
	s_add_u32 s33, s33, 0x100
	s_addc_u32 s80, s80, 0
	s_cmp_gt_u32 s81, 29
	s_barrier
	s_cbranch_scc0 .LBB0_259
	s_cmp_lg_u32 s12, s46
	v_lshl_add_u32 v144, s12, 8, v1
	s_cselect_b64 s[42:43], -1, 0
	s_mov_b64 s[24:25], -1
	s_and_b64 vcc, exec, s[42:43]
	v_ashrrev_i32_e32 v145, 31, v144
	s_cbranch_vccz .LBB0_262
	v_lshl_add_u64 v[142:143], v[144:145], 2, s[0:1]
	v_add_co_u32_e32 v152, vcc, 0x8000, v142
	global_load_dword v146, v[142:143], off
	s_nop 0
	v_addc_co_u32_e32 v153, vcc, 0, v143, vcc
	global_load_dword v151, v[152:153], off
	v_add_co_u32_e32 v152, vcc, 0x10000, v142
	s_mov_b64 s[24:25], 0
	s_nop 0
	v_addc_co_u32_e32 v153, vcc, 0, v143, vcc
	s_waitcnt vmcnt(0)
	v_add_f32_e32 v146, 0, v146
	v_add_f32_e32 v146, v146, v151
	global_load_dword v151, v[152:153], off
	v_add_co_u32_e32 v152, vcc, 0x18000, v142
	s_waitcnt vmcnt(0)
	v_add_f32_e32 v146, v146, v151
	v_addc_co_u32_e32 v153, vcc, 0, v143, vcc
	global_load_dword v151, v[152:153], off
	v_add_co_u32_e32 v152, vcc, s5, v142
	s_waitcnt vmcnt(0)
	v_add_f32_e32 v146, v146, v151
	v_addc_co_u32_e32 v153, vcc, 0, v143, vcc
	global_load_dword v151, v[152:153], off
	v_add_co_u32_e32 v152, vcc, 0x28000, v142
	s_waitcnt vmcnt(0)
	v_add_f32_e32 v146, v146, v151
	v_addc_co_u32_e32 v153, vcc, 0, v143, vcc
	global_load_dword v151, v[152:153], off
	v_add_co_u32_e32 v152, vcc, 0x30000, v142
	s_waitcnt vmcnt(0)
	v_add_f32_e32 v146, v146, v151
	v_addc_co_u32_e32 v153, vcc, 0, v143, vcc
	v_add_co_u32_e32 v142, vcc, 0x38000, v142
	global_load_dword v151, v[152:153], off
	s_nop 0
	v_addc_co_u32_e32 v143, vcc, 0, v143, vcc
	global_load_dword v142, v[142:143], off
	s_waitcnt vmcnt(0)
	v_add_f32_e32 v146, v146, v151
	v_add_f32_e32 v142, v146, v142
	v_fmamk_f32 v142, v142, 0x3a000000, v223
	v_cmp_gt_f32_e32 vcc, s4, v142
	v_mul_f32_e32 v143, 0x4b800000, v142
	s_nop 0
	v_cndmask_b32_e32 v142, v142, v143, vcc
	v_rsq_f32_e32 v142, v142
	s_nop 0
	v_mul_f32_e32 v143, 0x45800000, v142
	v_cndmask_b32_e32 v146, v142, v143, vcc
